# plus: 64B-align the two bisection loop heads
# baseline (speedup 1.0000x reference)
; __device__ __forceinline__ void topk_list(const unsigned (&uk)[32], LAS int* list, LAS float* listr, LAS unsigned* listT, const GAS f32x4* sak, int lane) {
;     unsigned T = 0u;
; __device__ __forceinline__ void att_unit(LAS unsigned char* lds, const bf16* P, const bf16* AKV, const bf16* IKC, bf16* ACAT, const float* aqg, const float* ssq_ak, const float* ssq_ik, int b, int qg, int tid) {
;     ...
;                     const float rscale = rsqrtf((rc[r4].x + rc[r4].y) * (1.f / 64.f) + EPS);
;                     const bool live = 64 * rr + lane < L;
; #pragma unroll
;                     for (int q = 0; q < 2; ++q) {
;                         float hx; const float A = half_sum32(pt[q][0], pt[q][2], hx), B = half_sum32(pt[q][1], pt[q][3], hx);
;                         const bool odd = fq & 1;
;                         const float send = odd ? A : B, keep = odd ? B : A;
;                         const float sc = live ? (keep + __shfl_xor(send, 16)) * rscale : -INFINITY;
;                         const unsigned bts = __float_as_uint(sc);
;                         uk[q][rr] = bts ^ ((unsigned)((int)bts >> 31) | 0x80000000u);
.LBB0_746:
	s_or_b64 exec, exec, s[2:3]
	v_ashrrev_i32_e32 v2, 31, v150
	s_brev_b32 s0, 1
	s_waitcnt vmcnt(7)
	v_bitop3_b32 v18, v2, v150, s0 bitop3:0x36
	v_ashrrev_i32_e32 v2, 31, v146
	v_bitop3_b32 v16, v2, v146, s0 bitop3:0x36
	v_ashrrev_i32_e32 v2, 31, v141
	v_bitop3_b32 v15, v2, v141, s0 bitop3:0x36
	v_ashrrev_i32_e32 v2, 31, v140
	v_bitop3_b32 v13, v2, v140, s0 bitop3:0x36
	s_mov_b32 s0, 0x45800000
	v_pk_mul_f32 v[2:3], v[94:95], s[0:1] op_sel_hi:[1,0]
	v_cndmask_b32_e64 v5, v69, v71, s[6:7]
	v_cndmask_b32_e64 v4, v68, v70, s[6:7]
	v_cndmask_b32_e64 v3, v95, v3, s[10:11]
	v_cndmask_b32_e64 v2, v94, v2, s[8:9]
	v_pk_add_f32 v[4:5], v[4:5], v[72:73]
	v_writelane_b32 v254, s82, 53
	v_pk_mul_f32 v[4:5], v[2:3], v[4:5]
	s_nop 0
	v_ashrrev_i32_e32 v6, 31, v5
	v_ashrrev_i32_e32 v7, 31, v4
	v_or_b32_e32 v6, 0x80000000, v6
	v_or_b32_e32 v7, 0x80000000, v7
	v_writelane_b32 v254, s83, 54
	v_xor_b32_e32 v9, v6, v5
	v_xor_b32_e32 v8, v7, v4
	v_pk_mul_f32 v[4:5], v[92:93], s[0:1] op_sel_hi:[1,0]
	v_cndmask_b32_e64 v7, v83, v87, s[6:7]
	v_cndmask_b32_e64 v6, v82, v86, s[6:7]
	v_writelane_b32 v254, s76, 51
	v_cndmask_b32_e64 v5, v93, v5, s[14:15]
	v_cndmask_b32_e64 v4, v92, v4, s[12:13]
	v_pk_add_f32 v[6:7], v[6:7], v[84:85]
	v_writelane_b32 v254, s77, 52
	v_pk_mul_f32 v[6:7], v[4:5], v[6:7]
	v_writelane_b32 v254, s74, 49
	v_ashrrev_i32_e32 v10, 31, v7
	v_ashrrev_i32_e32 v11, 31, v6
	v_writelane_b32 v254, s70, 47
	v_or_b32_e32 v10, 0x80000000, v10
	v_or_b32_e32 v11, 0x80000000, v11
	v_writelane_b32 v254, s71, 48
	v_xor_b32_e32 v7, v10, v7
	v_xor_b32_e32 v6, v11, v6
	v_mov_b32_e32 v10, 31
	v_mov_b32_e32 v85, 0
	.p2align 6

; __device__ __forceinline__ void topk_list(const unsigned (&uk)[32], LAS int* list, LAS float* listr, LAS unsigned* listT, const GAS f32x4* sak, int lane) {
;     unsigned T = 0u;
; __device__ __forceinline__ void att_unit(LAS unsigned char* lds, const bf16* P, const bf16* AKV, const bf16* IKC, bf16* ACAT, const float* aqg, const float* ssq_ak, const float* ssq_ik, int b, int qg, int tid) {
;     ...
;                     const float rscale = rsqrtf((rc[r4].x + rc[r4].y) * (1.f / 64.f) + EPS);
;                     const bool live = 64 * rr + lane < L;
; #pragma unroll
;                     for (int q = 0; q < 2; ++q) {
;                         float hx; const float A = half_sum32(pt[q][0], pt[q][2], hx), B = half_sum32(pt[q][1], pt[q][3], hx);
;                         const bool odd = fq & 1;
;                         const float send = odd ? A : B, keep = odd ? B : A;
;                         const float sc = live ? (keep + __shfl_xor(send, 16)) * rscale : -INFINITY;
;                         const unsigned bts = __float_as_uint(sc);
;                         uk[q][rr] = bts ^ ((unsigned)((int)bts >> 31) | 0x80000000u);
.LBB0_876:
	s_or_b64 exec, exec, s[2:3]
	v_ashrrev_i32_e32 v6, 31, v122
	s_brev_b32 s0, 1
	v_bitop3_b32 v87, v6, v122, s0 bitop3:0x36
	v_ashrrev_i32_e32 v6, 31, v121
	v_bitop3_b32 v88, v6, v121, s0 bitop3:0x36
	v_ashrrev_i32_e32 v6, 31, v116
	v_bitop3_b32 v89, v6, v116, s0 bitop3:0x36
	v_ashrrev_i32_e32 v6, 31, v115
	s_waitcnt vmcnt(0)
	v_bitop3_b32 v90, v6, v115, s0 bitop3:0x36
	v_cndmask_b32_e64 v7, v55, v59, s[6:7]
	v_cndmask_b32_e64 v6, v54, v58, s[6:7]
	v_pk_add_f32 v[6:7], v[6:7], v[56:57]
	s_nop 0
	v_pk_mul_f32 v[2:3], v[2:3], v[6:7]
	s_nop 0
	v_ashrrev_i32_e32 v6, 31, v3
	v_ashrrev_i32_e32 v7, 31, v2
	v_or_b32_e32 v6, 0x80000000, v6
	v_or_b32_e32 v54, 0x80000000, v7
	v_xor_b32_e32 v7, v6, v3
	v_xor_b32_e32 v6, v54, v2
	v_cndmask_b32_e64 v3, v61, v65, s[6:7]
	v_cndmask_b32_e64 v2, v60, v64, s[6:7]
	v_pk_add_f32 v[2:3], v[2:3], v[62:63]
	s_nop 0
	v_pk_mul_f32 v[2:3], v[4:5], v[2:3]
	s_nop 0
	v_ashrrev_i32_e32 v4, 31, v3
	v_ashrrev_i32_e32 v5, 31, v2
	v_or_b32_e32 v4, 0x80000000, v4
	v_or_b32_e32 v5, 0x80000000, v5
	v_xor_b32_e32 v3, v4, v3
	v_xor_b32_e32 v2, v5, v2
	v_mov_b32_e32 v5, 31
	v_mov_b32_e32 v4, 0
	.p2align 6
